# SwiGLU epilogue: per-pass compute interleaved with LDS staging/barriers/stores of the previous pass
# speedup vs baseline: 1.0035x; 1.0035x over previous
.LBB0_736:
	v_mov_b32_e32 v140, v145
	s_mov_b32 s17, s79
	v_mov_b32_e32 v141, v144
	s_mov_b32 s19, s62
	s_lshl_b32 s24, s24, 8
	s_lshl_b32 s19, s19, 6
	s_add_i32 s19, s19, s24
	v_add_u32_e32 v148, s19, v141
	s_lshl_b32 s19, s25, 7
	s_lshl_b32 s17, s17, 4
	s_add_i32 s17, s17, s19
	v_lshl_add_u32 v142, v140, 2, s17
	v_ashrrev_i32_e32 v143, 31, v142
	v_mov_b64_e32 v[140:141], s[6:7]
	v_mad_i64_i32 v[150:151], s[24:25], v148, s47, v[140:141]
	v_lshlrev_b64 v[142:143], 1, v[142:143]
	v_lshl_add_u64 v[150:151], v[150:151], 0, v[142:143]
	s_andn2_b64 vcc, exec, s[2:3]
	v_mul_f32_e32 v152, 0xbfb8aa3b, v126
	v_mul_f32_e32 v153, 0xbfb8aa3b, v127
	v_mul_f32_e32 v154, 0xbfb8aa3b, v128
	v_mul_f32_e32 v155, 0xbfb8aa3b, v129
	v_mul_f32_e32 v156, 0xbfb8aa3b, v118
	v_mul_f32_e32 v157, 0xbfb8aa3b, v119
	v_mul_f32_e32 v158, 0xbfb8aa3b, v120
	v_mul_f32_e32 v159, 0xbfb8aa3b, v121
	v_exp_f32_e32 v152, v152
	v_exp_f32_e32 v153, v153
	v_exp_f32_e32 v154, v154
	v_exp_f32_e32 v155, v155
	v_exp_f32_e32 v156, v156
	v_exp_f32_e32 v157, v157
	v_exp_f32_e32 v158, v158
	v_exp_f32_e32 v159, v159
	v_add_f32_e32 v152, 1.0, v152
	v_add_f32_e32 v153, 1.0, v153
	v_add_f32_e32 v154, 1.0, v154
	v_add_f32_e32 v155, 1.0, v155
	v_add_f32_e32 v156, 1.0, v156
	v_add_f32_e32 v157, 1.0, v157
	v_add_f32_e32 v158, 1.0, v158
	v_add_f32_e32 v159, 1.0, v159
	v_rcp_f32_e32 v152, v152
	v_rcp_f32_e32 v153, v153
	v_rcp_f32_e32 v154, v154
	v_rcp_f32_e32 v155, v155
	v_rcp_f32_e32 v156, v156
	v_rcp_f32_e32 v157, v157
	v_rcp_f32_e32 v158, v158
	v_rcp_f32_e32 v159, v159
	v_mul_f32_e32 v152, v126, v152
	v_mul_f32_e32 v153, v127, v153
	v_mul_f32_e32 v154, v128, v154
	v_mul_f32_e32 v155, v129, v155
	v_mul_f32_e32 v156, v118, v156
	v_mul_f32_e32 v157, v119, v157
	v_mul_f32_e32 v158, v120, v158
	v_mul_f32_e32 v159, v121, v159
	v_mul_f32_e32 v122, v122, v152
	v_mul_f32_e32 v123, v123, v153
	v_mul_f32_e32 v124, v124, v154
	v_mul_f32_e32 v125, v125, v155
	v_mul_f32_e32 v114, v114, v156
	v_mul_f32_e32 v115, v115, v157
	v_mul_f32_e32 v116, v116, v158
	v_mul_f32_e32 v117, v117, v159
	v_cvt_pk_bf16_f32 v122, v122, v123
	v_cvt_pk_bf16_f32 v123, v124, v125
	v_cvt_pk_bf16_f32 v114, v114, v115
	v_cvt_pk_bf16_f32 v115, v116, v117
	v_mul_f32_e32 v152, 0xbfb8aa3b, v110
	v_mul_f32_e32 v153, 0xbfb8aa3b, v111
	v_mul_f32_e32 v154, 0xbfb8aa3b, v112
	v_mul_f32_e32 v155, 0xbfb8aa3b, v113
	v_mul_f32_e32 v156, 0xbfb8aa3b, v102
	v_mul_f32_e32 v157, 0xbfb8aa3b, v103
	v_mul_f32_e32 v158, 0xbfb8aa3b, v104
	v_mul_f32_e32 v159, 0xbfb8aa3b, v105
	v_exp_f32_e32 v152, v152
	v_exp_f32_e32 v153, v153
	v_exp_f32_e32 v154, v154
	v_exp_f32_e32 v155, v155
	v_exp_f32_e32 v156, v156
	v_exp_f32_e32 v157, v157
	v_exp_f32_e32 v158, v158
	v_exp_f32_e32 v159, v159
	v_add_f32_e32 v152, 1.0, v152
	v_add_f32_e32 v153, 1.0, v153
	v_add_f32_e32 v154, 1.0, v154
	v_add_f32_e32 v155, 1.0, v155
	v_add_f32_e32 v156, 1.0, v156
	v_add_f32_e32 v157, 1.0, v157
	v_add_f32_e32 v158, 1.0, v158
	v_add_f32_e32 v159, 1.0, v159
	v_rcp_f32_e32 v152, v152
	v_rcp_f32_e32 v153, v153
	v_rcp_f32_e32 v154, v154
	v_rcp_f32_e32 v155, v155
	v_rcp_f32_e32 v156, v156
	v_rcp_f32_e32 v157, v157
	v_rcp_f32_e32 v158, v158
	v_rcp_f32_e32 v159, v159
	v_mul_f32_e32 v152, v110, v152
	v_mul_f32_e32 v153, v111, v153
	v_mul_f32_e32 v154, v112, v154
	v_mul_f32_e32 v155, v113, v155
	v_mul_f32_e32 v156, v102, v156
	v_mul_f32_e32 v157, v103, v157
	v_mul_f32_e32 v158, v104, v158
	v_mul_f32_e32 v159, v105, v159
	v_mul_f32_e32 v106, v106, v152
	v_mul_f32_e32 v107, v107, v153
	v_mul_f32_e32 v108, v108, v154
	v_mul_f32_e32 v109, v109, v155
	v_mul_f32_e32 v98, v98, v156
	v_mul_f32_e32 v99, v99, v157
	v_mul_f32_e32 v100, v100, v158
	v_mul_f32_e32 v101, v101, v159
	v_cvt_pk_bf16_f32 v106, v106, v107
	v_cvt_pk_bf16_f32 v107, v108, v109
	v_cvt_pk_bf16_f32 v98, v98, v99
	v_cvt_pk_bf16_f32 v99, v100, v101
	v_and_b32_e32 v160, 7, v144
	v_lshlrev_b32_e32 v160, 1, v160
	s_lshl_b32 s100, s79, 2
	v_add_u32_e32 v161, s100, v145
	v_xor_b32_e32 v161, v161, v160
	v_lshlrev_b32_e32 v161, 3, v161
	v_lshl_add_u32 v161, v144, 8, v161
	s_lshl_b32 s100, s62, 13
	s_add_i32 s100, s100, 49152
	v_add_u32_e32 v161, s100, v161
	v_add_u32_e32 v167, 98304, v161
	v_xor_b32_e32 v162, v144, v145
	v_lshlrev_b32_e32 v162, 4, v162
	s_lshl_b32 s101, s79, 11
	s_add_i32 s101, s101, s100
	v_lshl_add_u32 v163, v145, 8, s101
	v_add_u32_e32 v164, v163, v162
	v_or_b32_e32 v165, 4, v145
	v_xor_b32_e32 v165, v144, v165
	v_lshl_add_u32 v165, v165, 4, v163
	v_add_u32_e32 v174, 98304, v164
	v_add_u32_e32 v175, 98304, v165
	v_sub_u32_e32 v166, v148, v144
	s_lshl_b32 s101, s79, 3
	v_add3_u32 v166, v166, s101, v145
	v_mov_b64_e32 v[170:171], s[6:7]
	v_mad_u64_u32 v[168:169], s[100:101], v166, s47, v[170:171]
	s_lshl_b32 s101, s79, 5
	v_subrev_u32_e32 v172, s101, v142
	v_lshlrev_b32_e32 v173, 3, v145
	v_sub_u32_e32 v172, v172, v173
	v_lshl_add_u32 v172, v144, 4, v172
	v_mov_b32_e32 v173, 0
	v_lshl_add_u64 v[168:169], v[168:169], 0, v[172:173]
	s_mov_b32 s101, 0
	ds_write_b64 v161, v[122:123] offset:0
	ds_write_b64 v161, v[114:115] offset:128
	ds_write_b64 v161, v[106:107] offset:4096
	ds_write_b64 v161, v[98:99] offset:4224
	v_mul_f32_e32 v152, 0xbfb8aa3b, v92
	v_mul_f32_e32 v153, 0xbfb8aa3b, v93
	v_mul_f32_e32 v154, 0xbfb8aa3b, v94
	v_mul_f32_e32 v155, 0xbfb8aa3b, v95
	v_mul_f32_e32 v156, 0xbfb8aa3b, v84
	v_mul_f32_e32 v157, 0xbfb8aa3b, v85
	v_mul_f32_e32 v158, 0xbfb8aa3b, v86
	v_mul_f32_e32 v159, 0xbfb8aa3b, v87
	v_exp_f32_e32 v152, v152
	v_exp_f32_e32 v153, v153
	v_exp_f32_e32 v154, v154
	v_exp_f32_e32 v155, v155
	v_exp_f32_e32 v156, v156
	v_exp_f32_e32 v157, v157
	v_exp_f32_e32 v158, v158
	v_exp_f32_e32 v159, v159
	v_add_f32_e32 v152, 1.0, v152
	v_add_f32_e32 v153, 1.0, v153
	v_add_f32_e32 v154, 1.0, v154
	v_add_f32_e32 v155, 1.0, v155
	v_add_f32_e32 v156, 1.0, v156
	v_add_f32_e32 v157, 1.0, v157
	v_add_f32_e32 v158, 1.0, v158
	v_add_f32_e32 v159, 1.0, v159
	v_rcp_f32_e32 v152, v152
	v_rcp_f32_e32 v153, v153
	v_rcp_f32_e32 v154, v154
	v_rcp_f32_e32 v155, v155
	v_rcp_f32_e32 v156, v156
	v_rcp_f32_e32 v157, v157
	v_rcp_f32_e32 v158, v158
	v_rcp_f32_e32 v159, v159
	v_mul_f32_e32 v152, v92, v152
	v_mul_f32_e32 v153, v93, v153
	v_mul_f32_e32 v154, v94, v154
	v_mul_f32_e32 v155, v95, v155
	v_mul_f32_e32 v156, v84, v156
	v_mul_f32_e32 v157, v85, v157
	v_mul_f32_e32 v158, v86, v158
	v_mul_f32_e32 v159, v87, v159
	v_mul_f32_e32 v88, v88, v152
	v_mul_f32_e32 v89, v89, v153
	v_mul_f32_e32 v90, v90, v154
	v_mul_f32_e32 v91, v91, v155
	v_mul_f32_e32 v80, v80, v156
	v_mul_f32_e32 v81, v81, v157
	v_mul_f32_e32 v82, v82, v158
	v_mul_f32_e32 v83, v83, v159
	v_cvt_pk_bf16_f32 v88, v88, v89
	v_cvt_pk_bf16_f32 v89, v90, v91
	v_cvt_pk_bf16_f32 v80, v80, v81
	v_cvt_pk_bf16_f32 v81, v82, v83
	v_mul_f32_e32 v152, 0xbfb8aa3b, v76
	v_mul_f32_e32 v153, 0xbfb8aa3b, v77
	v_mul_f32_e32 v154, 0xbfb8aa3b, v78
	v_mul_f32_e32 v155, 0xbfb8aa3b, v79
	v_mul_f32_e32 v156, 0xbfb8aa3b, v68
	v_mul_f32_e32 v157, 0xbfb8aa3b, v69
	v_mul_f32_e32 v158, 0xbfb8aa3b, v70
	v_mul_f32_e32 v159, 0xbfb8aa3b, v71
	v_exp_f32_e32 v152, v152
	v_exp_f32_e32 v153, v153
	v_exp_f32_e32 v154, v154
	v_exp_f32_e32 v155, v155
	v_exp_f32_e32 v156, v156
	v_exp_f32_e32 v157, v157
	v_exp_f32_e32 v158, v158
	v_exp_f32_e32 v159, v159
	v_add_f32_e32 v152, 1.0, v152
	v_add_f32_e32 v153, 1.0, v153
	v_add_f32_e32 v154, 1.0, v154
	v_add_f32_e32 v155, 1.0, v155
	v_add_f32_e32 v156, 1.0, v156
	v_add_f32_e32 v157, 1.0, v157
	v_add_f32_e32 v158, 1.0, v158
	v_add_f32_e32 v159, 1.0, v159
	v_rcp_f32_e32 v152, v152
	v_rcp_f32_e32 v153, v153
	v_rcp_f32_e32 v154, v154
	v_rcp_f32_e32 v155, v155
	v_rcp_f32_e32 v156, v156
	v_rcp_f32_e32 v157, v157
	v_rcp_f32_e32 v158, v158
	v_rcp_f32_e32 v159, v159
	v_mul_f32_e32 v152, v76, v152
	v_mul_f32_e32 v153, v77, v153
	v_mul_f32_e32 v154, v78, v154
	v_mul_f32_e32 v155, v79, v155
	v_mul_f32_e32 v156, v68, v156
	v_mul_f32_e32 v157, v69, v157
	v_mul_f32_e32 v158, v70, v158
	v_mul_f32_e32 v159, v71, v159
	v_mul_f32_e32 v72, v72, v152
	v_mul_f32_e32 v73, v73, v153
	v_mul_f32_e32 v74, v74, v154
	v_mul_f32_e32 v75, v75, v155
	v_mul_f32_e32 v64, v64, v156
	v_mul_f32_e32 v65, v65, v157
	v_mul_f32_e32 v66, v66, v158
	v_mul_f32_e32 v67, v67, v159
	v_cvt_pk_bf16_f32 v72, v72, v73
	v_cvt_pk_bf16_f32 v73, v74, v75
	v_cvt_pk_bf16_f32 v64, v64, v65
	v_cvt_pk_bf16_f32 v65, v66, v67
	s_waitcnt lgkmcnt(0)
	s_barrier
	ds_read_b128 v[176:179], v164
	ds_read_b128 v[180:183], v165 offset:1024
	s_waitcnt lgkmcnt(1)
	global_store_dwordx4 v[168:169], v[176:179], off
	s_mov_b32 s100, 22528
	v_lshl_add_u64 v[168:169], v[168:169], 0, s[100:101]
	s_waitcnt lgkmcnt(0)
	global_store_dwordx4 v[168:169], v[180:183], off
	s_mov_b32 s100, 157696
	v_lshl_add_u64 v[168:169], v[168:169], 0, s[100:101]
	s_nop 1
	ds_write_b64 v167, v[88:89] offset:0
	ds_write_b64 v167, v[80:81] offset:128
	ds_write_b64 v167, v[72:73] offset:4096
	ds_write_b64 v167, v[64:65] offset:4224
	v_mul_f32_e32 v152, 0xbfb8aa3b, v60
	v_mul_f32_e32 v153, 0xbfb8aa3b, v61
	v_mul_f32_e32 v154, 0xbfb8aa3b, v62
	v_mul_f32_e32 v155, 0xbfb8aa3b, v63
	v_mul_f32_e32 v156, 0xbfb8aa3b, v52
	v_mul_f32_e32 v157, 0xbfb8aa3b, v53
	v_mul_f32_e32 v158, 0xbfb8aa3b, v54
	v_mul_f32_e32 v159, 0xbfb8aa3b, v55
	v_exp_f32_e32 v152, v152
	v_exp_f32_e32 v153, v153
	v_exp_f32_e32 v154, v154
	v_exp_f32_e32 v155, v155
	v_exp_f32_e32 v156, v156
	v_exp_f32_e32 v157, v157
	v_exp_f32_e32 v158, v158
	v_exp_f32_e32 v159, v159
	v_add_f32_e32 v152, 1.0, v152
	v_add_f32_e32 v153, 1.0, v153
	v_add_f32_e32 v154, 1.0, v154
	v_add_f32_e32 v155, 1.0, v155
	v_add_f32_e32 v156, 1.0, v156
	v_add_f32_e32 v157, 1.0, v157
	v_add_f32_e32 v158, 1.0, v158
	v_add_f32_e32 v159, 1.0, v159
	v_rcp_f32_e32 v152, v152
	v_rcp_f32_e32 v153, v153
	v_rcp_f32_e32 v154, v154
	v_rcp_f32_e32 v155, v155
	v_rcp_f32_e32 v156, v156
	v_rcp_f32_e32 v157, v157
	v_rcp_f32_e32 v158, v158
	v_rcp_f32_e32 v159, v159
	v_mul_f32_e32 v152, v60, v152
	v_mul_f32_e32 v153, v61, v153
	v_mul_f32_e32 v154, v62, v154
	v_mul_f32_e32 v155, v63, v155
	v_mul_f32_e32 v156, v52, v156
	v_mul_f32_e32 v157, v53, v157
	v_mul_f32_e32 v158, v54, v158
	v_mul_f32_e32 v159, v55, v159
	v_mul_f32_e32 v56, v56, v152
	v_mul_f32_e32 v57, v57, v153
	v_mul_f32_e32 v58, v58, v154
	v_mul_f32_e32 v59, v59, v155
	v_mul_f32_e32 v48, v48, v156
	v_mul_f32_e32 v49, v49, v157
	v_mul_f32_e32 v50, v50, v158
	v_mul_f32_e32 v51, v51, v159
	v_cvt_pk_bf16_f32 v56, v56, v57
	v_cvt_pk_bf16_f32 v57, v58, v59
	v_cvt_pk_bf16_f32 v48, v48, v49
	v_cvt_pk_bf16_f32 v49, v50, v51
	v_mul_f32_e32 v152, 0xbfb8aa3b, v44
	v_mul_f32_e32 v153, 0xbfb8aa3b, v45
	v_mul_f32_e32 v154, 0xbfb8aa3b, v46
	v_mul_f32_e32 v155, 0xbfb8aa3b, v47
	v_mul_f32_e32 v156, 0xbfb8aa3b, v36
	v_mul_f32_e32 v157, 0xbfb8aa3b, v37
	v_mul_f32_e32 v158, 0xbfb8aa3b, v38
	v_mul_f32_e32 v159, 0xbfb8aa3b, v39
	v_exp_f32_e32 v152, v152
	v_exp_f32_e32 v153, v153
	v_exp_f32_e32 v154, v154
	v_exp_f32_e32 v155, v155
	v_exp_f32_e32 v156, v156
	v_exp_f32_e32 v157, v157
	v_exp_f32_e32 v158, v158
	v_exp_f32_e32 v159, v159
	v_add_f32_e32 v152, 1.0, v152
	v_add_f32_e32 v153, 1.0, v153
	v_add_f32_e32 v154, 1.0, v154
	v_add_f32_e32 v155, 1.0, v155
	v_add_f32_e32 v156, 1.0, v156
	v_add_f32_e32 v157, 1.0, v157
	v_add_f32_e32 v158, 1.0, v158
	v_add_f32_e32 v159, 1.0, v159
	v_rcp_f32_e32 v152, v152
	v_rcp_f32_e32 v153, v153
	v_rcp_f32_e32 v154, v154
	v_rcp_f32_e32 v155, v155
	v_rcp_f32_e32 v156, v156
	v_rcp_f32_e32 v157, v157
	v_rcp_f32_e32 v158, v158
	v_rcp_f32_e32 v159, v159
	v_mul_f32_e32 v152, v44, v152
	v_mul_f32_e32 v153, v45, v153
	v_mul_f32_e32 v154, v46, v154
	v_mul_f32_e32 v155, v47, v155
	v_mul_f32_e32 v156, v36, v156
	v_mul_f32_e32 v157, v37, v157
	v_mul_f32_e32 v158, v38, v158
	v_mul_f32_e32 v159, v39, v159
	v_mul_f32_e32 v40, v40, v152
	v_mul_f32_e32 v41, v41, v153
	v_mul_f32_e32 v42, v42, v154
	v_mul_f32_e32 v43, v43, v155
	v_mul_f32_e32 v32, v32, v156
	v_mul_f32_e32 v33, v33, v157
	v_mul_f32_e32 v34, v34, v158
	v_mul_f32_e32 v35, v35, v159
	v_cvt_pk_bf16_f32 v40, v40, v41
	v_cvt_pk_bf16_f32 v41, v42, v43
	v_cvt_pk_bf16_f32 v32, v32, v33
	v_cvt_pk_bf16_f32 v33, v34, v35
	s_waitcnt lgkmcnt(0)
	s_barrier
	ds_read_b128 v[176:179], v174
	ds_read_b128 v[180:183], v175 offset:1024
	s_waitcnt lgkmcnt(1)
	global_store_dwordx4 v[168:169], v[176:179], off
	s_mov_b32 s100, 22528
	v_lshl_add_u64 v[168:169], v[168:169], 0, s[100:101]
	s_waitcnt lgkmcnt(0)
	global_store_dwordx4 v[168:169], v[180:183], off
	s_mov_b32 s100, 518144
	v_lshl_add_u64 v[168:169], v[168:169], 0, s[100:101]
	s_nop 1
	ds_write_b64 v161, v[56:57] offset:0
	ds_write_b64 v161, v[48:49] offset:128
	ds_write_b64 v161, v[40:41] offset:4096
	ds_write_b64 v161, v[32:33] offset:4224
	v_mul_f32_e32 v152, 0xbfb8aa3b, v28
	v_mul_f32_e32 v153, 0xbfb8aa3b, v29
	v_mul_f32_e32 v154, 0xbfb8aa3b, v30
	v_mul_f32_e32 v155, 0xbfb8aa3b, v31
	v_mul_f32_e32 v156, 0xbfb8aa3b, v20
	v_mul_f32_e32 v157, 0xbfb8aa3b, v21
	v_mul_f32_e32 v158, 0xbfb8aa3b, v22
	v_mul_f32_e32 v159, 0xbfb8aa3b, v23
	v_exp_f32_e32 v152, v152
	v_exp_f32_e32 v153, v153
	v_exp_f32_e32 v154, v154
	v_exp_f32_e32 v155, v155
	v_exp_f32_e32 v156, v156
	v_exp_f32_e32 v157, v157
	v_exp_f32_e32 v158, v158
	v_exp_f32_e32 v159, v159
	v_add_f32_e32 v152, 1.0, v152
	v_add_f32_e32 v153, 1.0, v153
	v_add_f32_e32 v154, 1.0, v154
	v_add_f32_e32 v155, 1.0, v155
	v_add_f32_e32 v156, 1.0, v156
	v_add_f32_e32 v157, 1.0, v157
	v_add_f32_e32 v158, 1.0, v158
	v_add_f32_e32 v159, 1.0, v159
	v_rcp_f32_e32 v152, v152
	v_rcp_f32_e32 v153, v153
	v_rcp_f32_e32 v154, v154
	v_rcp_f32_e32 v155, v155
	v_rcp_f32_e32 v156, v156
	v_rcp_f32_e32 v157, v157
	v_rcp_f32_e32 v158, v158
	v_rcp_f32_e32 v159, v159
	v_mul_f32_e32 v152, v28, v152
	v_mul_f32_e32 v153, v29, v153
	v_mul_f32_e32 v154, v30, v154
	v_mul_f32_e32 v155, v31, v155
	v_mul_f32_e32 v156, v20, v156
	v_mul_f32_e32 v157, v21, v157
	v_mul_f32_e32 v158, v22, v158
	v_mul_f32_e32 v159, v23, v159
	v_mul_f32_e32 v24, v24, v152
	v_mul_f32_e32 v25, v25, v153
	v_mul_f32_e32 v26, v26, v154
	v_mul_f32_e32 v27, v27, v155
	v_mul_f32_e32 v16, v16, v156
	v_mul_f32_e32 v17, v17, v157
	v_mul_f32_e32 v18, v18, v158
	v_mul_f32_e32 v19, v19, v159
	v_cvt_pk_bf16_f32 v24, v24, v25
	v_cvt_pk_bf16_f32 v25, v26, v27
	v_cvt_pk_bf16_f32 v16, v16, v17
	v_cvt_pk_bf16_f32 v17, v18, v19
	s_mov_b64 s[24:25], -1
	v_mul_f32_e32 v152, 0xbfb8aa3b, v12
	v_mul_f32_e32 v153, 0xbfb8aa3b, v13
	v_mul_f32_e32 v154, 0xbfb8aa3b, v14
	v_mul_f32_e32 v155, 0xbfb8aa3b, v15
	v_mul_f32_e32 v156, 0xbfb8aa3b, v4
	v_mul_f32_e32 v157, 0xbfb8aa3b, v5
	v_mul_f32_e32 v158, 0xbfb8aa3b, v6
	v_mul_f32_e32 v159, 0xbfb8aa3b, v7
	v_exp_f32_e32 v152, v152
	v_exp_f32_e32 v153, v153
	v_exp_f32_e32 v154, v154
	v_exp_f32_e32 v155, v155
	v_exp_f32_e32 v156, v156
	v_exp_f32_e32 v157, v157
	v_exp_f32_e32 v158, v158
	v_exp_f32_e32 v159, v159
	v_add_f32_e32 v152, 1.0, v152
	v_add_f32_e32 v153, 1.0, v153
	v_add_f32_e32 v154, 1.0, v154
	v_add_f32_e32 v155, 1.0, v155
	v_add_f32_e32 v156, 1.0, v156
	v_add_f32_e32 v157, 1.0, v157
	v_add_f32_e32 v158, 1.0, v158
	v_add_f32_e32 v159, 1.0, v159
	v_rcp_f32_e32 v152, v152
	v_rcp_f32_e32 v153, v153
	v_rcp_f32_e32 v154, v154
	v_rcp_f32_e32 v155, v155
	v_rcp_f32_e32 v156, v156
	v_rcp_f32_e32 v157, v157
	v_rcp_f32_e32 v158, v158
	v_rcp_f32_e32 v159, v159
	v_mul_f32_e32 v152, v12, v152
	v_mul_f32_e32 v153, v13, v153
	v_mul_f32_e32 v154, v14, v154
	v_mul_f32_e32 v155, v15, v155
	v_mul_f32_e32 v156, v4, v156
	v_mul_f32_e32 v157, v5, v157
	v_mul_f32_e32 v158, v6, v158
	v_mul_f32_e32 v159, v7, v159
	v_mul_f32_e32 v8, v8, v152
	v_mul_f32_e32 v9, v9, v153
	v_mul_f32_e32 v10, v10, v154
	v_mul_f32_e32 v11, v11, v155
	v_mul_f32_e32 v0, v0, v156
	v_mul_f32_e32 v1, v1, v157
	v_mul_f32_e32 v2, v2, v158
	v_mul_f32_e32 v3, v3, v159
	v_cvt_pk_bf16_f32 v8, v8, v9
	v_cvt_pk_bf16_f32 v9, v10, v11
	v_cvt_pk_bf16_f32 v0, v0, v1
	v_cvt_pk_bf16_f32 v1, v2, v3
	s_waitcnt lgkmcnt(0)
	s_barrier
	ds_read_b128 v[176:179], v164
	ds_read_b128 v[180:183], v165 offset:1024
	s_waitcnt lgkmcnt(1)
	global_store_dwordx4 v[168:169], v[176:179], off
	s_mov_b32 s100, 22528
	v_lshl_add_u64 v[168:169], v[168:169], 0, s[100:101]
	s_waitcnt lgkmcnt(0)
	global_store_dwordx4 v[168:169], v[180:183], off
	s_mov_b32 s100, 157696
	v_lshl_add_u64 v[168:169], v[168:169], 0, s[100:101]
	s_nop 1
	ds_write_b64 v167, v[24:25] offset:0
	ds_write_b64 v167, v[16:17] offset:128
	ds_write_b64 v167, v[8:9] offset:4096
	ds_write_b64 v167, v[0:1] offset:4224
	s_waitcnt lgkmcnt(0)
	s_barrier
	ds_read_b128 v[176:179], v174
	ds_read_b128 v[180:183], v175 offset:1024
	s_waitcnt lgkmcnt(1)
	global_store_dwordx4 v[168:169], v[176:179], off
	s_mov_b32 s100, 22528
	v_lshl_add_u64 v[168:169], v[168:169], 0, s[100:101]
	s_waitcnt lgkmcnt(0)
	global_store_dwordx4 v[168:169], v[180:183], off
	s_nop 1
	s_cbranch_vccnz .LBB0_729
	s_andn2_b64 vcc, exec, s[4:5]
	s_cbranch_vccnz .LBB0_728
	s_barrier
	s_branch .LBB0_728
